# attention: first-half softmax tail interleaved into the second-half QK MFMA chain (defer8)
# baseline (speedup 1.0000x reference)
.Lnd_107:
	s_and_b32 s33, s42, 1
	s_mul_i32 s6, s33, 0x9000
	v_add_u32_e32 v199, s6, v187
	v_add_u32_e32 v198, s6, v188
	s_mov_b64 s[54:55], exec
	v_readfirstlane_b32 s4, v186
	s_bitcmp1_b32 s4, 8
	s_cbranch_scc1 .Lab_B
	ds_read_b128 v[216:219], v199 offset:0
	ds_read_b128 v[232:235], v193 offset:0
	ds_read_b128 v[220:223], v199 offset:32
	ds_read_b128 v[236:239], v193 offset:32
	ds_read_b128 v[224:227], v199 offset:64
	ds_read_b128 v[244:247], v193 offset:64
	ds_read_b128 v[228:231], v199 offset:96
	ds_read_b128 v[248:251], v193 offset:96
	s_waitcnt lgkmcnt(6)
	v_mfma_f32_32x32x16_bf16 v[144:159], v[216:219], v[232:235], v[0:15]
	s_waitcnt lgkmcnt(4)
	v_mfma_f32_32x32x16_bf16 v[144:159], v[220:223], v[236:239], v[144:159]
	s_waitcnt lgkmcnt(2)
	v_mfma_f32_32x32x16_bf16 v[144:159], v[224:227], v[244:247], v[144:159]
	s_waitcnt lgkmcnt(0)
	v_mfma_f32_32x32x16_bf16 v[144:159], v[228:231], v[248:251], v[144:159]
	ds_read_b128 v[216:219], v199 offset:9216
	ds_read_b128 v[232:235], v193 offset:36864
	ds_read_b128 v[220:223], v199 offset:9248
	ds_read_b128 v[236:239], v193 offset:36896
	ds_read_b128 v[224:227], v199 offset:9280
	ds_read_b128 v[244:247], v193 offset:36928
	ds_read_b128 v[228:231], v199 offset:9312
	ds_read_b128 v[248:251], v193 offset:36960
	s_nop 3
	v_exp_f32_e32 v144, v144
	v_exp_f32_e32 v145, v145
	v_exp_f32_e32 v146, v146
	v_exp_f32_e32 v147, v147
	v_exp_f32_e32 v148, v148
	v_exp_f32_e32 v149, v149
	v_exp_f32_e32 v150, v150
	v_exp_f32_e32 v151, v151
	v_exp_f32_e32 v152, v152
	v_exp_f32_e32 v153, v153
	v_exp_f32_e32 v154, v154
	v_exp_f32_e32 v155, v155
	v_exp_f32_e32 v156, v156
	v_exp_f32_e32 v157, v157
	v_exp_f32_e32 v158, v158
	v_exp_f32_e32 v159, v159
	v_add_f32_e32 v243, v144, v145
	v_add_f32_e32 v243, v146, v243
	v_add_f32_e32 v243, v147, v243
	v_add_f32_e32 v243, v148, v243
	v_add_f32_e32 v243, v149, v243
	v_add_f32_e32 v243, v150, v243
	v_add_f32_e32 v243, v151, v243
	s_waitcnt lgkmcnt(6)
	v_mfma_f32_32x32x16_bf16 v[200:215], v[216:219], v[232:235], v[0:15]
	v_add_f32_e32 v243, v152, v243
	v_add_f32_e32 v243, v153, v243
	v_add_f32_e32 v243, v154, v243
	v_add_f32_e32 v243, v155, v243
	s_waitcnt lgkmcnt(4)
	v_mfma_f32_32x32x16_bf16 v[200:215], v[220:223], v[236:239], v[200:215]
	v_add_f32_e32 v243, v156, v243
	v_add_f32_e32 v243, v157, v243
	v_add_f32_e32 v243, v158, v243
	v_add_f32_e32 v243, v159, v243
	s_waitcnt lgkmcnt(2)
	v_mfma_f32_32x32x16_bf16 v[200:215], v[224:227], v[244:247], v[200:215]
	v_add_f32_e32 v196, v196, v243
	v_cvt_pk_bf16_f32 v144, v144, v145
	v_cvt_pk_bf16_f32 v145, v146, v147
	v_cvt_pk_bf16_f32 v146, v148, v149
	s_waitcnt lgkmcnt(0)
	v_mfma_f32_32x32x16_bf16 v[200:215], v[228:231], v[248:251], v[200:215]
	ds_read_b128 v[216:219], v198 offset:0
	ds_read_b128 v[224:227], v198 offset:4608
	ds_read_b128 v[232:235], v198 offset:9216
	ds_read_b128 v[244:247], v198 offset:13824
	ds_read_b128 v[220:223], v198 offset:32
	ds_read_b128 v[228:231], v198 offset:4640
	ds_read_b128 v[236:239], v198 offset:9248
	ds_read_b128 v[248:251], v198 offset:13856
	v_cvt_pk_bf16_f32 v147, v150, v151
	v_cvt_pk_bf16_f32 v148, v152, v153
	v_cvt_pk_bf16_f32 v149, v154, v155
	v_cvt_pk_bf16_f32 v150, v156, v157
	v_cvt_pk_bf16_f32 v151, v158, v159
	s_waitcnt lgkmcnt(7)
	v_mfma_f32_32x32x16_bf16 v[112:127], v[216:219], v[144:147], v[112:127]
	v_exp_f32_e32 v200, v200
	v_exp_f32_e32 v201, v201
	v_exp_f32_e32 v202, v202
	v_exp_f32_e32 v203, v203
	v_exp_f32_e32 v204, v204
	s_waitcnt lgkmcnt(6)
	v_mfma_f32_32x32x16_bf16 v[80:95], v[224:227], v[144:147], v[80:95]
	v_exp_f32_e32 v205, v205
	v_exp_f32_e32 v206, v206
	v_exp_f32_e32 v207, v207
	v_exp_f32_e32 v208, v208
	v_exp_f32_e32 v209, v209
	s_waitcnt lgkmcnt(5)
	v_mfma_f32_32x32x16_bf16 v[48:63], v[232:235], v[144:147], v[48:63]
	v_exp_f32_e32 v210, v210
	v_exp_f32_e32 v211, v211
	v_exp_f32_e32 v212, v212
	v_exp_f32_e32 v213, v213
	v_exp_f32_e32 v214, v214
	s_waitcnt lgkmcnt(4)
	v_mfma_f32_32x32x16_bf16 v[16:31], v[244:247], v[144:147], v[16:31]
	v_exp_f32_e32 v215, v215
	v_add_f32_e32 v243, v200, v201
	v_add_f32_e32 v243, v202, v243
	v_add_f32_e32 v243, v203, v243
	v_add_f32_e32 v243, v204, v243
	s_waitcnt lgkmcnt(3)
	v_mfma_f32_32x32x16_bf16 v[112:127], v[220:223], v[148:151], v[112:127]
	v_add_f32_e32 v243, v205, v243
	v_add_f32_e32 v243, v206, v243
	v_add_f32_e32 v243, v207, v243
	v_add_f32_e32 v243, v208, v243
	v_add_f32_e32 v243, v209, v243
	s_waitcnt lgkmcnt(2)
	v_mfma_f32_32x32x16_bf16 v[80:95], v[228:231], v[148:151], v[80:95]
	v_add_f32_e32 v243, v210, v243
	v_add_f32_e32 v243, v211, v243
	v_add_f32_e32 v243, v212, v243
	v_add_f32_e32 v243, v213, v243
	v_add_f32_e32 v243, v214, v243
	s_waitcnt lgkmcnt(1)
	v_mfma_f32_32x32x16_bf16 v[48:63], v[236:239], v[148:151], v[48:63]
	v_add_f32_e32 v243, v215, v243
	v_add_f32_e32 v197, v197, v243
	v_cvt_pk_bf16_f32 v200, v200, v201
	v_cvt_pk_bf16_f32 v201, v202, v203
	v_cvt_pk_bf16_f32 v202, v204, v205
	s_waitcnt lgkmcnt(0)
	v_mfma_f32_32x32x16_bf16 v[16:31], v[248:251], v[148:151], v[16:31]
	v_cvt_pk_bf16_f32 v203, v206, v207
	v_cvt_pk_bf16_f32 v204, v208, v209
	v_cvt_pk_bf16_f32 v205, v210, v211
	v_cvt_pk_bf16_f32 v206, v212, v213
	v_cvt_pk_bf16_f32 v207, v214, v215
	s_nop 1
	v_mfma_f32_32x32x16_bf16 v[128:143], v[216:219], v[200:203], v[128:143]
	v_mfma_f32_32x32x16_bf16 v[96:111], v[224:227], v[200:203], v[96:111]
	v_mfma_f32_32x32x16_bf16 v[64:79], v[232:235], v[200:203], v[64:79]
	v_mfma_f32_32x32x16_bf16 v[32:47], v[244:247], v[200:203], v[32:47]
	v_mfma_f32_32x32x16_bf16 v[128:143], v[220:223], v[204:207], v[128:143]
	v_mfma_f32_32x32x16_bf16 v[96:111], v[228:231], v[204:207], v[96:111]
	v_mfma_f32_32x32x16_bf16 v[64:79], v[236:239], v[204:207], v[64:79]
	v_mfma_f32_32x32x16_bf16 v[32:47], v[248:251], v[204:207], v[32:47]
	ds_read_b128 v[216:219], v199 offset:4608
	ds_read_b128 v[232:235], v193 offset:0
	ds_read_b128 v[220:223], v199 offset:4640
	ds_read_b128 v[236:239], v193 offset:32
	ds_read_b128 v[224:227], v199 offset:4672
	ds_read_b128 v[244:247], v193 offset:64
	ds_read_b128 v[228:231], v199 offset:4704
	ds_read_b128 v[248:251], v193 offset:96
	s_waitcnt lgkmcnt(6)
	v_mfma_f32_32x32x16_bf16 v[144:159], v[216:219], v[232:235], v[0:15]
	s_waitcnt lgkmcnt(4)
	v_mfma_f32_32x32x16_bf16 v[144:159], v[220:223], v[236:239], v[144:159]
	s_waitcnt lgkmcnt(2)
	v_mfma_f32_32x32x16_bf16 v[144:159], v[224:227], v[244:247], v[144:159]
	s_waitcnt lgkmcnt(0)
	v_mfma_f32_32x32x16_bf16 v[144:159], v[228:231], v[248:251], v[144:159]
	ds_read_b128 v[216:219], v199 offset:13824
	ds_read_b128 v[232:235], v193 offset:36864
	ds_read_b128 v[220:223], v199 offset:13856
	ds_read_b128 v[236:239], v193 offset:36896
	ds_read_b128 v[224:227], v199 offset:13888
	ds_read_b128 v[244:247], v193 offset:36928
	ds_read_b128 v[228:231], v199 offset:13920
	ds_read_b128 v[248:251], v193 offset:36960
	s_nop 3
	v_exp_f32_e32 v144, v144
	v_exp_f32_e32 v145, v145
	v_exp_f32_e32 v146, v146
	v_exp_f32_e32 v147, v147
	v_exp_f32_e32 v148, v148
	v_exp_f32_e32 v149, v149
	v_exp_f32_e32 v150, v150
	v_exp_f32_e32 v151, v151
	v_exp_f32_e32 v152, v152
	v_exp_f32_e32 v153, v153
	v_exp_f32_e32 v154, v154
	v_exp_f32_e32 v155, v155
	v_exp_f32_e32 v156, v156
	v_exp_f32_e32 v157, v157
	v_exp_f32_e32 v158, v158
	v_exp_f32_e32 v159, v159
	v_add_f32_e32 v243, v144, v145
	v_add_f32_e32 v243, v146, v243
	v_add_f32_e32 v243, v147, v243
	v_add_f32_e32 v243, v148, v243
	v_add_f32_e32 v243, v149, v243
	v_add_f32_e32 v243, v150, v243
	v_add_f32_e32 v243, v151, v243
	s_waitcnt lgkmcnt(6)
	v_mfma_f32_32x32x16_bf16 v[200:215], v[216:219], v[232:235], v[0:15]
	v_add_f32_e32 v243, v152, v243
	v_add_f32_e32 v243, v153, v243
	v_add_f32_e32 v243, v154, v243
	v_add_f32_e32 v243, v155, v243
	s_waitcnt lgkmcnt(4)
	v_mfma_f32_32x32x16_bf16 v[200:215], v[220:223], v[236:239], v[200:215]
	v_add_f32_e32 v243, v156, v243
	v_add_f32_e32 v243, v157, v243
	v_add_f32_e32 v243, v158, v243
	v_add_f32_e32 v243, v159, v243
	s_waitcnt lgkmcnt(2)
	v_mfma_f32_32x32x16_bf16 v[200:215], v[224:227], v[244:247], v[200:215]
	v_add_f32_e32 v196, v196, v243
	v_cvt_pk_bf16_f32 v144, v144, v145
	v_cvt_pk_bf16_f32 v145, v146, v147
	v_cvt_pk_bf16_f32 v146, v148, v149
	s_waitcnt lgkmcnt(0)
	v_mfma_f32_32x32x16_bf16 v[200:215], v[228:231], v[248:251], v[200:215]
	ds_read_b128 v[216:219], v198 offset:64
	ds_read_b128 v[224:227], v198 offset:4672
	ds_read_b128 v[232:235], v198 offset:9280
	ds_read_b128 v[244:247], v198 offset:13888
	ds_read_b128 v[220:223], v198 offset:96
	ds_read_b128 v[228:231], v198 offset:4704
	ds_read_b128 v[236:239], v198 offset:9312
	ds_read_b128 v[248:251], v198 offset:13920
	v_cvt_pk_bf16_f32 v147, v150, v151
	v_cvt_pk_bf16_f32 v148, v152, v153
	v_cvt_pk_bf16_f32 v149, v154, v155
	v_cvt_pk_bf16_f32 v150, v156, v157
	v_cvt_pk_bf16_f32 v151, v158, v159
	s_waitcnt lgkmcnt(7)
	v_mfma_f32_32x32x16_bf16 v[112:127], v[216:219], v[144:147], v[112:127]
	v_exp_f32_e32 v200, v200
	v_exp_f32_e32 v201, v201
	v_exp_f32_e32 v202, v202
	v_exp_f32_e32 v203, v203
	v_exp_f32_e32 v204, v204
	s_waitcnt lgkmcnt(6)
	v_mfma_f32_32x32x16_bf16 v[80:95], v[224:227], v[144:147], v[80:95]
	v_exp_f32_e32 v205, v205
	v_exp_f32_e32 v206, v206
	v_exp_f32_e32 v207, v207
	v_exp_f32_e32 v208, v208
	v_exp_f32_e32 v209, v209
	s_waitcnt lgkmcnt(5)
	v_mfma_f32_32x32x16_bf16 v[48:63], v[232:235], v[144:147], v[48:63]
	v_exp_f32_e32 v210, v210
	v_exp_f32_e32 v211, v211
	v_exp_f32_e32 v212, v212
	v_exp_f32_e32 v213, v213
	v_exp_f32_e32 v214, v214
	s_waitcnt lgkmcnt(4)
	v_mfma_f32_32x32x16_bf16 v[16:31], v[244:247], v[144:147], v[16:31]
	v_exp_f32_e32 v215, v215
	v_add_f32_e32 v243, v200, v201
	v_add_f32_e32 v243, v202, v243
	v_add_f32_e32 v243, v203, v243
	v_add_f32_e32 v243, v204, v243
	s_waitcnt lgkmcnt(3)
	v_mfma_f32_32x32x16_bf16 v[112:127], v[220:223], v[148:151], v[112:127]
	v_add_f32_e32 v243, v205, v243
	v_add_f32_e32 v243, v206, v243
	v_add_f32_e32 v243, v207, v243
	v_add_f32_e32 v243, v208, v243
	v_add_f32_e32 v243, v209, v243
	s_waitcnt lgkmcnt(2)
	v_mfma_f32_32x32x16_bf16 v[80:95], v[228:231], v[148:151], v[80:95]
	v_add_f32_e32 v243, v210, v243
	v_add_f32_e32 v243, v211, v243
	v_add_f32_e32 v243, v212, v243
	v_add_f32_e32 v243, v213, v243
	v_add_f32_e32 v243, v214, v243
	s_waitcnt lgkmcnt(1)
	v_mfma_f32_32x32x16_bf16 v[48:63], v[236:239], v[148:151], v[48:63]
	v_add_f32_e32 v243, v215, v243
	v_add_f32_e32 v197, v197, v243
	v_cvt_pk_bf16_f32 v200, v200, v201
	v_cvt_pk_bf16_f32 v201, v202, v203
	v_cvt_pk_bf16_f32 v202, v204, v205
	s_waitcnt lgkmcnt(0)
	v_mfma_f32_32x32x16_bf16 v[16:31], v[248:251], v[148:151], v[16:31]
	v_cvt_pk_bf16_f32 v203, v206, v207
	v_cvt_pk_bf16_f32 v204, v208, v209
	v_cvt_pk_bf16_f32 v205, v210, v211
	v_cvt_pk_bf16_f32 v206, v212, v213
	v_cvt_pk_bf16_f32 v207, v214, v215
	s_nop 1
	v_mfma_f32_32x32x16_bf16 v[128:143], v[216:219], v[200:203], v[128:143]
	v_mfma_f32_32x32x16_bf16 v[96:111], v[224:227], v[200:203], v[96:111]
	v_mfma_f32_32x32x16_bf16 v[64:79], v[232:235], v[200:203], v[64:79]
	v_mfma_f32_32x32x16_bf16 v[32:47], v[244:247], v[200:203], v[32:47]
	v_mfma_f32_32x32x16_bf16 v[128:143], v[220:223], v[204:207], v[128:143]
	v_mfma_f32_32x32x16_bf16 v[96:111], v[228:231], v[204:207], v[96:111]
	v_mfma_f32_32x32x16_bf16 v[64:79], v[236:239], v[204:207], v[64:79]
	v_mfma_f32_32x32x16_bf16 v[32:47], v[248:251], v[204:207], v[32:47]
	s_branch .LBB0_111

.Lab_B0:
	ds_read_b128 v[216:219], v199 offset:0
	ds_read_b128 v[232:235], v193 offset:0
	ds_read_b128 v[220:223], v199 offset:32
	ds_read_b128 v[236:239], v193 offset:32
	ds_read_b128 v[224:227], v199 offset:64
	ds_read_b128 v[244:247], v193 offset:64
	ds_read_b128 v[228:231], v199 offset:96
	ds_read_b128 v[248:251], v193 offset:96
	s_waitcnt lgkmcnt(6)
	v_mfma_f32_32x32x16_bf16 v[144:159], v[216:219], v[232:235], v[0:15]
	s_waitcnt lgkmcnt(4)
	v_mfma_f32_32x32x16_bf16 v[144:159], v[220:223], v[236:239], v[144:159]
	s_waitcnt lgkmcnt(2)
	v_mfma_f32_32x32x16_bf16 v[144:159], v[224:227], v[244:247], v[144:159]
	s_waitcnt lgkmcnt(0)
	v_mfma_f32_32x32x16_bf16 v[144:159], v[228:231], v[248:251], v[144:159]
	ds_read_b128 v[216:219], v199 offset:9216
	ds_read_b128 v[232:235], v193 offset:36864
	ds_read_b128 v[220:223], v199 offset:9248
	ds_read_b128 v[236:239], v193 offset:36896
	ds_read_b128 v[224:227], v199 offset:9280
	ds_read_b128 v[244:247], v193 offset:36928
	ds_read_b128 v[228:231], v199 offset:9312
	ds_read_b128 v[248:251], v193 offset:36960
	s_nop 3
	v_exp_f32_e32 v144, v144
	v_exp_f32_e32 v145, v145
	v_exp_f32_e32 v146, v146
	v_exp_f32_e32 v147, v147
	v_exp_f32_e32 v148, v148
	v_exp_f32_e32 v149, v149
	v_exp_f32_e32 v150, v150
	v_exp_f32_e32 v151, v151
	v_exp_f32_e32 v152, v152
	v_exp_f32_e32 v153, v153
	v_exp_f32_e32 v154, v154
	v_exp_f32_e32 v155, v155
	v_exp_f32_e32 v156, v156
	v_exp_f32_e32 v157, v157
	v_exp_f32_e32 v158, v158
	v_exp_f32_e32 v159, v159
	v_add_f32_e32 v243, v144, v145
	v_add_f32_e32 v243, v146, v243
	v_add_f32_e32 v243, v147, v243
	v_add_f32_e32 v243, v148, v243
	v_add_f32_e32 v243, v149, v243
	v_add_f32_e32 v243, v150, v243
	v_add_f32_e32 v243, v151, v243
	s_waitcnt lgkmcnt(6)
	v_mfma_f32_32x32x16_bf16 v[200:215], v[216:219], v[232:235], v[0:15]
	v_add_f32_e32 v243, v152, v243
	v_add_f32_e32 v243, v153, v243
	v_add_f32_e32 v243, v154, v243
	v_add_f32_e32 v243, v155, v243
	s_waitcnt lgkmcnt(4)
	v_mfma_f32_32x32x16_bf16 v[200:215], v[220:223], v[236:239], v[200:215]
	v_add_f32_e32 v243, v156, v243
	v_add_f32_e32 v243, v157, v243
	v_add_f32_e32 v243, v158, v243
	v_add_f32_e32 v243, v159, v243
	s_waitcnt lgkmcnt(2)
	v_mfma_f32_32x32x16_bf16 v[200:215], v[224:227], v[244:247], v[200:215]
	v_add_f32_e32 v196, v196, v243
	v_cvt_pk_bf16_f32 v144, v144, v145
	v_cvt_pk_bf16_f32 v145, v146, v147
	v_cvt_pk_bf16_f32 v146, v148, v149
	s_waitcnt lgkmcnt(0)
	v_mfma_f32_32x32x16_bf16 v[200:215], v[228:231], v[248:251], v[200:215]
	ds_read_b128 v[216:219], v198 offset:0
	ds_read_b128 v[224:227], v198 offset:4608
	ds_read_b128 v[232:235], v198 offset:9216
	ds_read_b128 v[244:247], v198 offset:13824
	ds_read_b128 v[220:223], v198 offset:32
	ds_read_b128 v[228:231], v198 offset:4640
	ds_read_b128 v[236:239], v198 offset:9248
	ds_read_b128 v[248:251], v198 offset:13856
	v_cvt_pk_bf16_f32 v147, v150, v151
	v_cvt_pk_bf16_f32 v148, v152, v153
	v_cvt_pk_bf16_f32 v149, v154, v155
	v_cvt_pk_bf16_f32 v150, v156, v157
	v_cvt_pk_bf16_f32 v151, v158, v159
	s_waitcnt lgkmcnt(7)
	v_mfma_f32_32x32x16_bf16 v[112:127], v[216:219], v[144:147], v[112:127]
	v_exp_f32_e32 v200, v200
	v_exp_f32_e32 v201, v201
	v_exp_f32_e32 v202, v202
	v_exp_f32_e32 v203, v203
	v_exp_f32_e32 v204, v204
	s_waitcnt lgkmcnt(6)
	v_mfma_f32_32x32x16_bf16 v[80:95], v[224:227], v[144:147], v[80:95]
	v_exp_f32_e32 v205, v205
	v_exp_f32_e32 v206, v206
	v_exp_f32_e32 v207, v207
	v_exp_f32_e32 v208, v208
	v_exp_f32_e32 v209, v209
	s_waitcnt lgkmcnt(5)
	v_mfma_f32_32x32x16_bf16 v[48:63], v[232:235], v[144:147], v[48:63]
	v_exp_f32_e32 v210, v210
	v_exp_f32_e32 v211, v211
	v_exp_f32_e32 v212, v212
	v_exp_f32_e32 v213, v213
	v_exp_f32_e32 v214, v214
	s_waitcnt lgkmcnt(4)
	v_mfma_f32_32x32x16_bf16 v[16:31], v[244:247], v[144:147], v[16:31]
	v_exp_f32_e32 v215, v215
	v_add_f32_e32 v243, v200, v201
	v_add_f32_e32 v243, v202, v243
	v_add_f32_e32 v243, v203, v243
	v_add_f32_e32 v243, v204, v243
	s_waitcnt lgkmcnt(3)
	v_mfma_f32_32x32x16_bf16 v[112:127], v[220:223], v[148:151], v[112:127]
	v_add_f32_e32 v243, v205, v243
	v_add_f32_e32 v243, v206, v243
	v_add_f32_e32 v243, v207, v243
	v_add_f32_e32 v243, v208, v243
	v_add_f32_e32 v243, v209, v243
	s_waitcnt lgkmcnt(2)
	v_mfma_f32_32x32x16_bf16 v[80:95], v[228:231], v[148:151], v[80:95]
	v_add_f32_e32 v243, v210, v243
	v_add_f32_e32 v243, v211, v243
	v_add_f32_e32 v243, v212, v243
	v_add_f32_e32 v243, v213, v243
	v_add_f32_e32 v243, v214, v243
	s_waitcnt lgkmcnt(1)
	v_mfma_f32_32x32x16_bf16 v[48:63], v[236:239], v[148:151], v[48:63]
	v_add_f32_e32 v243, v215, v243
	v_add_f32_e32 v197, v197, v243
	v_cvt_pk_bf16_f32 v200, v200, v201
	v_cvt_pk_bf16_f32 v201, v202, v203
	v_cvt_pk_bf16_f32 v202, v204, v205
	s_waitcnt lgkmcnt(0)
	v_mfma_f32_32x32x16_bf16 v[16:31], v[248:251], v[148:151], v[16:31]
	v_cvt_pk_bf16_f32 v203, v206, v207
	v_cvt_pk_bf16_f32 v204, v208, v209
	v_cvt_pk_bf16_f32 v205, v210, v211
	v_cvt_pk_bf16_f32 v206, v212, v213
	v_cvt_pk_bf16_f32 v207, v214, v215
	s_nop 1
	v_mfma_f32_32x32x16_bf16 v[128:143], v[216:219], v[200:203], v[128:143]
	v_mfma_f32_32x32x16_bf16 v[96:111], v[224:227], v[200:203], v[96:111]
	v_mfma_f32_32x32x16_bf16 v[64:79], v[232:235], v[200:203], v[64:79]
	v_mfma_f32_32x32x16_bf16 v[32:47], v[244:247], v[200:203], v[32:47]
	v_mfma_f32_32x32x16_bf16 v[128:143], v[220:223], v[204:207], v[128:143]
	v_mfma_f32_32x32x16_bf16 v[96:111], v[228:231], v[204:207], v[96:111]
	v_mfma_f32_32x32x16_bf16 v[64:79], v[236:239], v[204:207], v[64:79]
	v_mfma_f32_32x32x16_bf16 v[32:47], v[248:251], v[204:207], v[32:47]
	ds_read_b128 v[216:219], v199 offset:4608
	ds_read_b128 v[232:235], v193 offset:0
	ds_read_b128 v[220:223], v199 offset:4640
	ds_read_b128 v[236:239], v193 offset:32
	ds_read_b128 v[224:227], v199 offset:4672
	ds_read_b128 v[244:247], v193 offset:64
	ds_read_b128 v[228:231], v199 offset:4704
	ds_read_b128 v[248:251], v193 offset:96
	s_waitcnt lgkmcnt(6)
	v_mfma_f32_32x32x16_bf16 v[144:159], v[216:219], v[232:235], v[0:15]
	s_waitcnt lgkmcnt(4)
	v_mfma_f32_32x32x16_bf16 v[144:159], v[220:223], v[236:239], v[144:159]
	s_waitcnt lgkmcnt(2)
	v_mfma_f32_32x32x16_bf16 v[144:159], v[224:227], v[244:247], v[144:159]
	s_waitcnt lgkmcnt(0)
	v_mfma_f32_32x32x16_bf16 v[144:159], v[228:231], v[248:251], v[144:159]
	ds_read_b128 v[216:219], v199 offset:13824
	ds_read_b128 v[232:235], v193 offset:36864
	ds_read_b128 v[220:223], v199 offset:13856
	ds_read_b128 v[236:239], v193 offset:36896
	ds_read_b128 v[224:227], v199 offset:13888
	ds_read_b128 v[244:247], v193 offset:36928
	ds_read_b128 v[228:231], v199 offset:13920
	ds_read_b128 v[248:251], v193 offset:36960
	s_nop 3
	v_exp_f32_e32 v144, v144
	v_exp_f32_e32 v145, v145
	v_exp_f32_e32 v146, v146
	v_exp_f32_e32 v147, v147
	v_exp_f32_e32 v148, v148
	v_exp_f32_e32 v149, v149
	v_exp_f32_e32 v150, v150
	v_exp_f32_e32 v151, v151
	v_exp_f32_e32 v152, v152
	v_exp_f32_e32 v153, v153
	v_exp_f32_e32 v154, v154
	v_exp_f32_e32 v155, v155
	v_exp_f32_e32 v156, v156
	v_exp_f32_e32 v157, v157
	v_exp_f32_e32 v158, v158
	v_exp_f32_e32 v159, v159
	v_add_f32_e32 v243, v144, v145
	v_add_f32_e32 v243, v146, v243
	v_add_f32_e32 v243, v147, v243
	v_add_f32_e32 v243, v148, v243
	v_add_f32_e32 v243, v149, v243
	v_add_f32_e32 v243, v150, v243
	v_add_f32_e32 v243, v151, v243
	s_waitcnt lgkmcnt(6)
	v_mfma_f32_32x32x16_bf16 v[200:215], v[216:219], v[232:235], v[0:15]
	v_add_f32_e32 v243, v152, v243
	v_add_f32_e32 v243, v153, v243
	v_add_f32_e32 v243, v154, v243
	v_add_f32_e32 v243, v155, v243
	s_waitcnt lgkmcnt(4)
	v_mfma_f32_32x32x16_bf16 v[200:215], v[220:223], v[236:239], v[200:215]
	v_add_f32_e32 v243, v156, v243
	v_add_f32_e32 v243, v157, v243
	v_add_f32_e32 v243, v158, v243
	v_add_f32_e32 v243, v159, v243
	s_waitcnt lgkmcnt(2)
	v_mfma_f32_32x32x16_bf16 v[200:215], v[224:227], v[244:247], v[200:215]
	v_add_f32_e32 v196, v196, v243
	v_cvt_pk_bf16_f32 v144, v144, v145
	v_cvt_pk_bf16_f32 v145, v146, v147
	v_cvt_pk_bf16_f32 v146, v148, v149
	s_waitcnt lgkmcnt(0)
	v_mfma_f32_32x32x16_bf16 v[200:215], v[228:231], v[248:251], v[200:215]
	ds_read_b128 v[216:219], v198 offset:64
	ds_read_b128 v[224:227], v198 offset:4672
	ds_read_b128 v[232:235], v198 offset:9280
	ds_read_b128 v[244:247], v198 offset:13888
	ds_read_b128 v[220:223], v198 offset:96
	ds_read_b128 v[228:231], v198 offset:4704
	ds_read_b128 v[236:239], v198 offset:9312
	ds_read_b128 v[248:251], v198 offset:13920
	v_cvt_pk_bf16_f32 v147, v150, v151
	v_cvt_pk_bf16_f32 v148, v152, v153
	v_cvt_pk_bf16_f32 v149, v154, v155
	v_cvt_pk_bf16_f32 v150, v156, v157
	v_cvt_pk_bf16_f32 v151, v158, v159
	s_waitcnt lgkmcnt(7)
	v_mfma_f32_32x32x16_bf16 v[112:127], v[216:219], v[144:147], v[112:127]
	v_exp_f32_e32 v200, v200
	v_exp_f32_e32 v201, v201
	v_exp_f32_e32 v202, v202
	v_exp_f32_e32 v203, v203
	v_exp_f32_e32 v204, v204
	s_waitcnt lgkmcnt(6)
	v_mfma_f32_32x32x16_bf16 v[80:95], v[224:227], v[144:147], v[80:95]
	v_exp_f32_e32 v205, v205
	v_exp_f32_e32 v206, v206
	v_exp_f32_e32 v207, v207
	v_exp_f32_e32 v208, v208
	v_exp_f32_e32 v209, v209
	s_waitcnt lgkmcnt(5)
	v_mfma_f32_32x32x16_bf16 v[48:63], v[232:235], v[144:147], v[48:63]
	v_exp_f32_e32 v210, v210
	v_exp_f32_e32 v211, v211
	v_exp_f32_e32 v212, v212
	v_exp_f32_e32 v213, v213
	v_exp_f32_e32 v214, v214
	s_waitcnt lgkmcnt(4)
	v_mfma_f32_32x32x16_bf16 v[16:31], v[244:247], v[144:147], v[16:31]
	v_exp_f32_e32 v215, v215
	v_add_f32_e32 v243, v200, v201
	v_add_f32_e32 v243, v202, v243
	v_add_f32_e32 v243, v203, v243
	v_add_f32_e32 v243, v204, v243
	s_waitcnt lgkmcnt(3)
	v_mfma_f32_32x32x16_bf16 v[112:127], v[220:223], v[148:151], v[112:127]
	v_add_f32_e32 v243, v205, v243
	v_add_f32_e32 v243, v206, v243
	v_add_f32_e32 v243, v207, v243
	v_add_f32_e32 v243, v208, v243
	v_add_f32_e32 v243, v209, v243
	s_waitcnt lgkmcnt(2)
	v_mfma_f32_32x32x16_bf16 v[80:95], v[228:231], v[148:151], v[80:95]
	v_add_f32_e32 v243, v210, v243
	v_add_f32_e32 v243, v211, v243
	v_add_f32_e32 v243, v212, v243
	v_add_f32_e32 v243, v213, v243
	v_add_f32_e32 v243, v214, v243
	s_waitcnt lgkmcnt(1)
	v_mfma_f32_32x32x16_bf16 v[48:63], v[236:239], v[148:151], v[48:63]
	v_add_f32_e32 v243, v215, v243
	v_add_f32_e32 v197, v197, v243
	v_cvt_pk_bf16_f32 v200, v200, v201
	v_cvt_pk_bf16_f32 v201, v202, v203
	v_cvt_pk_bf16_f32 v202, v204, v205
	s_waitcnt lgkmcnt(0)
	v_mfma_f32_32x32x16_bf16 v[16:31], v[248:251], v[148:151], v[16:31]
	v_cvt_pk_bf16_f32 v203, v206, v207
	v_cvt_pk_bf16_f32 v204, v208, v209
	v_cvt_pk_bf16_f32 v205, v210, v211
	v_cvt_pk_bf16_f32 v206, v212, v213
	v_cvt_pk_bf16_f32 v207, v214, v215
	s_add_i32 s4, s42, 1
	s_cmp_lt_u32 s4, s98
	s_cbranch_scc1 .LBB0_111
	s_nop 1
	v_mfma_f32_32x32x16_bf16 v[128:143], v[216:219], v[200:203], v[128:143]
	v_mfma_f32_32x32x16_bf16 v[96:111], v[224:227], v[200:203], v[96:111]
	v_mfma_f32_32x32x16_bf16 v[64:79], v[232:235], v[200:203], v[64:79]
	v_mfma_f32_32x32x16_bf16 v[32:47], v[244:247], v[200:203], v[32:47]
	v_mfma_f32_32x32x16_bf16 v[128:143], v[220:223], v[204:207], v[128:143]
	v_mfma_f32_32x32x16_bf16 v[96:111], v[228:231], v[204:207], v[96:111]
	v_mfma_f32_32x32x16_bf16 v[64:79], v[236:239], v[204:207], v[64:79]
	v_mfma_f32_32x32x16_bf16 v[32:47], v[248:251], v[204:207], v[32:47]
	s_branch .LBB0_111
